# partial last round of each tile loop (gemmA, gate, merge, out, qkv) redistributed to one workgroup per CU across all XCDs instead of two per CU on half the XCDs; prefetch uses the same mapping
# speedup vs baseline: 1.0895x; 1.0109x over previous
.LBB0_193:
	s_add_i32 s2, s92, s85
	s_cmpk_lg_u32 s33, 0x200
	s_cbranch_scc1 .Lrm_done_1
	s_sub_i32 s3, 0x1680, s92
	s_cmpk_gt_i32 s3, 0x1ff
	s_cbranch_scc1 .Lrm_done_1
	s_cmpk_lt_i32 s3, 8
	s_cbranch_scc1 .Lrm_done_1
	s_lshr_b32 s3, s3, 3
	s_and_b32 s4, s85, 63
	s_movk_i32 s2, 0x1680
	s_cmp_ge_u32 s4, s3
	s_cbranch_scc1 .Lrm_done_1
	s_lshr_b32 s2, s85, 6
	s_mul_i32 s2, s2, s3
	s_add_i32 s2, s2, s4
	s_add_i32 s2, s2, s92
.Lrm_done_1:
	s_cmpk_gt_i32 s2, 0x167f
	s_cbranch_scc1 .LBB0_192
	s_ashr_i32 s3, s2, 5
	s_mul_hi_i32 s4, s3, 0x66666667
	s_lshr_b32 s5, s4, 31
	s_ashr_i32 s4, s4, 1
	s_add_i32 s5, s4, s5
	s_lshl_b32 s4, s5, 3
	s_bfe_u32 s8, s2, 0x30002
	s_or_b32 s4, s4, s8
	s_mul_i32 s5, s5, 5
	s_sub_i32 s3, s3, s5
	s_lshl_b32 s24, s4, 7
	s_lshl_b32 s3, s3, 2
	s_and_b32 s2, s2, 3
	s_ashr_i32 s25, s24, 31
	s_or_b32 s26, s3, s2
	s_lshl_b64 s[2:3], s[24:25], 11
	s_add_u32 s2, s64, s2
	s_addc_u32 s3, s86, s3
	s_ashr_i32 s27, s26, 31
	v_mov_b32_e32 v4, v111
	s_lshl_b64 s[8:9], s[26:27], 18
	s_add_u32 s8, s93, s8
	v_ashrrev_i32_e32 v0, 3, v4
	v_lshrrev_b32_e32 v6, 4, v4
	v_xor_b32_e32 v8, v6, v4
	v_ashrrev_i32_e32 v1, 31, v0
	s_addc_u32 s9, s20, s9
	v_lshlrev_b64 v[0:1], 11, v[0:1]
	v_lshlrev_b32_e32 v8, 4, v8
	v_lshl_add_u64 v[2:3], s[2:3], 0, v[0:1]
	v_and_b32_e32 v108, 0x70, v8
	v_lshl_add_u64 v[0:1], s[8:9], 0, v[0:1]
	s_waitcnt vmcnt(11)
	v_lshlrev_b32_e32 v83, 4, v4
	v_lshl_add_u64 v[66:67], v[0:1], 0, v[108:109]
	v_readfirstlane_b32 s2, v83
	v_add_u32_e32 v0, 0x1000, v83
	v_lshl_add_u64 v[64:65], v[2:3], 0, v[108:109]
	s_mov_b32 m0, s2
	s_mov_b64 s[8:9], 0x10000
	v_readfirstlane_b32 s2, v0
	v_add_u32_e32 v0, 0x2000, v83
	s_cmp_eq_u32 s100, 1
	s_cbranch_scc1 .Lpf_a_skip0
	global_load_lds_dwordx4 v[64:65], off

.LBB0_195:
	s_add_i32 s5, s2, 0xffff8000
	s_and_b32 s5, s5, 0x8000
	s_xor_b32 s3, s5, 0x8000
	s_add_u32 s3, s3, s16
	s_mov_b32 s8, s3
	s_mov_b32 m0, s8
	s_add_u32 s8, s3, 0x1000
	v_add_u32_e32 v85, s5, v81
	global_load_lds_dwordx4 v[64:65], off
	v_lshl_add_u64 v[64:65], v[64:65], 0, s[98:99]
	s_mov_b32 m0, s8
	s_add_u32 s8, s3, 0x2000
	v_or_b32_e32 v106, s5, v80
	global_load_lds_dwordx4 v[68:69], off
	v_lshl_add_u64 v[68:69], v[68:69], 0, s[98:99]
	s_mov_b32 m0, s8
	s_add_u32 s8, s3, 0x3000
	v_add_u32_e32 v250, v85, v84
	global_load_lds_dwordx4 v[70:71], off
	v_lshl_add_u64 v[70:71], v[70:71], 0, s[98:99]
	s_mov_b32 m0, s8
	s_add_u32 s8, s3, 0x4000
	v_add_u32_e32 v251, v106, v84
	global_load_lds_dwordx4 v[72:73], off
	v_lshl_add_u64 v[72:73], v[72:73], 0, s[98:99]
	s_mov_b32 m0, s8
	s_add_u32 s8, s3, 0x5000
	v_add_u32_e32 v252, v85, v82
	global_load_lds_dwordx4 v[66:67], off
	v_lshl_add_u64 v[66:67], v[66:67], 0, s[98:99]
	s_mov_b32 m0, s8
	s_add_u32 s8, s3, 0x6000
	v_add_u32_e32 v253, v106, v82
	global_load_lds_dwordx4 v[74:75], off
	v_lshl_add_u64 v[74:75], v[74:75], 0, s[98:99]
	s_mov_b32 m0, s8
	s_add_u32 s8, s3, 0x7000
	s_nop 0
	global_load_lds_dwordx4 v[76:77], off
	v_lshl_add_u64 v[76:77], v[76:77], 0, s[98:99]
	s_mov_b32 m0, s8
	s_add_u32 s8, s3, 0x8000
	s_nop 0
	global_load_lds_dwordx4 v[78:79], off
	v_lshl_add_u64 v[78:79], v[78:79], 0, s[98:99]
	ds_read_b128 v[86:89], v250
	ds_read_b128 v[102:105], v251 offset:16384
	ds_read_b128 v[122:125], v251 offset:18432
	ds_read_b128 v[126:129], v251 offset:20480
	ds_read_b128 v[130:133], v251 offset:22528
	ds_read_b128 v[90:93], v250 offset:2048
	ds_read_b128 v[94:97], v250 offset:4096
	ds_read_b128 v[98:101], v250 offset:6144
	ds_read_b128 v[218:221], v252
	ds_read_b128 v[234:237], v253 offset:16384
	ds_read_b128 v[238:241], v253 offset:18432
	ds_read_b128 v[242:245], v253 offset:20480
	ds_read_b128 v[246:249], v253 offset:22528
	ds_read_b128 v[222:225], v252 offset:2048
	ds_read_b128 v[226:229], v252 offset:4096
	s_waitcnt lgkmcnt(13)
	v_mfma_f32_16x16x32_bf16 v[60:63], v[86:89], v[102:105], v[60:63]
	ds_read_b128 v[230:233], v252 offset:6144
	s_waitcnt lgkmcnt(13)
	v_mfma_f32_16x16x32_bf16 v[56:59], v[86:89], v[122:125], v[56:59]
	s_waitcnt lgkmcnt(12)
	v_mfma_f32_16x16x32_bf16 v[52:55], v[86:89], v[126:129], v[52:55]
	s_waitcnt lgkmcnt(11)
	v_mfma_f32_16x16x32_bf16 v[48:51], v[86:89], v[130:133], v[48:51]
	s_waitcnt lgkmcnt(10)
	v_mfma_f32_16x16x32_bf16 v[44:47], v[90:93], v[102:105], v[44:47]
	v_mfma_f32_16x16x32_bf16 v[40:43], v[90:93], v[122:125], v[40:43]
	v_mfma_f32_16x16x32_bf16 v[36:39], v[90:93], v[126:129], v[36:39]
	v_mfma_f32_16x16x32_bf16 v[32:35], v[90:93], v[130:133], v[32:35]
	s_waitcnt lgkmcnt(9)
	v_mfma_f32_16x16x32_bf16 v[28:31], v[94:97], v[102:105], v[28:31]
	v_mfma_f32_16x16x32_bf16 v[24:27], v[94:97], v[122:125], v[24:27]
	v_mfma_f32_16x16x32_bf16 v[20:23], v[94:97], v[126:129], v[20:23]
	v_mfma_f32_16x16x32_bf16 v[16:19], v[94:97], v[130:133], v[16:19]
	s_waitcnt lgkmcnt(8)
	v_mfma_f32_16x16x32_bf16 v[12:15], v[98:101], v[102:105], v[12:15]
	v_mfma_f32_16x16x32_bf16 v[8:11], v[98:101], v[122:125], v[8:11]
	v_mfma_f32_16x16x32_bf16 v[4:7], v[98:101], v[126:129], v[4:7]
	v_mfma_f32_16x16x32_bf16 v[0:3], v[98:101], v[130:133], v[0:3]
	s_waitcnt lgkmcnt(6)
	v_mfma_f32_16x16x32_bf16 v[60:63], v[218:221], v[234:237], v[60:63]
	s_waitcnt lgkmcnt(5)
	v_mfma_f32_16x16x32_bf16 v[56:59], v[218:221], v[238:241], v[56:59]
	s_waitcnt lgkmcnt(4)
	v_mfma_f32_16x16x32_bf16 v[52:55], v[218:221], v[242:245], v[52:55]
	s_waitcnt lgkmcnt(3)
	v_mfma_f32_16x16x32_bf16 v[48:51], v[218:221], v[246:249], v[48:51]
	s_waitcnt lgkmcnt(2)
	v_mfma_f32_16x16x32_bf16 v[44:47], v[222:225], v[234:237], v[44:47]
	v_mfma_f32_16x16x32_bf16 v[40:43], v[222:225], v[238:241], v[40:43]
	v_mfma_f32_16x16x32_bf16 v[36:39], v[222:225], v[242:245], v[36:39]
	v_mfma_f32_16x16x32_bf16 v[32:35], v[222:225], v[246:249], v[32:35]
	s_waitcnt lgkmcnt(1)
	v_mfma_f32_16x16x32_bf16 v[28:31], v[226:229], v[234:237], v[28:31]
	v_mfma_f32_16x16x32_bf16 v[24:27], v[226:229], v[238:241], v[24:27]
	v_mfma_f32_16x16x32_bf16 v[20:23], v[226:229], v[242:245], v[20:23]
	v_mfma_f32_16x16x32_bf16 v[16:19], v[226:229], v[246:249], v[16:19]
	s_waitcnt lgkmcnt(0)
	v_mfma_f32_16x16x32_bf16 v[12:15], v[230:233], v[234:237], v[12:15]
	v_mfma_f32_16x16x32_bf16 v[8:11], v[230:233], v[238:241], v[8:11]
	v_mfma_f32_16x16x32_bf16 v[4:7], v[230:233], v[242:245], v[4:7]
	v_mfma_f32_16x16x32_bf16 v[0:3], v[230:233], v[246:249], v[0:3]
	s_add_i32 s2, s2, 0x8000
	s_cmp_lg_u32 s2, 0x80000
	s_waitcnt vmcnt(0)
	s_barrier
	s_cbranch_scc1 .LBB0_195
	s_mov_b32 s100, 0
	s_add_i32 s8, s92, s33
	s_add_i32 s2, s8, s85
	s_cmpk_lg_u32 s33, 0x200
	s_cbranch_scc1 .Lrm_done_5
	s_sub_i32 s3, 0x1680, s8
	s_cmpk_gt_i32 s3, 0x1ff
	s_cbranch_scc1 .Lrm_done_5
	s_cmpk_lt_i32 s3, 8
	s_cbranch_scc1 .Lrm_done_5
	s_lshr_b32 s3, s3, 3
	s_and_b32 s5, s85, 63
	s_movk_i32 s2, 0x1680
	s_cmp_ge_u32 s5, s3
	s_cbranch_scc1 .Lrm_done_5
	s_lshr_b32 s2, s85, 6
	s_mul_i32 s2, s2, s3
	s_add_i32 s2, s2, s5
	s_add_i32 s2, s2, s8
.Lrm_done_5:
	s_cmpk_gt_i32 s2, 0x167f
	s_cbranch_scc1 .Lpf_a_done
	s_ashr_i32 s3, s2, 5
	s_mul_hi_i32 s5, s3, 0x66666667
	s_lshr_b32 s8, s5, 31
	s_ashr_i32 s5, s5, 1
	s_add_i32 s5, s5, s8
	s_lshl_b32 s8, s5, 3
	s_bfe_u32 s9, s2, 0x30002
	s_or_b32 s8, s8, s9
	s_mul_i32 s5, s5, 5
	s_sub_i32 s3, s3, s5
	s_lshl_b32 s3, s3, 2
	s_and_b32 s9, s2, 3
	s_or_b32 s3, s3, s9
	s_lshr_b32 s9, s24, 7
	s_sub_i32 s8, s8, s9
	s_sub_i32 s2, s3, s26
	s_ashr_i32 s9, s8, 31
	s_lshl_b64 s[8:9], s[8:9], 18
	s_sub_u32 s8, s8, 0x800
	s_subb_u32 s9, s9, 0
	s_ashr_i32 s3, s2, 31
	s_lshl_b64 s[2:3], s[2:3], 18
	s_sub_u32 s2, s2, 0x800
	s_subb_u32 s3, s3, 0
	v_lshl_add_u64 v[250:251], v[64:65], 0, s[8:9]
	s_mov_b32 s5, s16
	s_mov_b32 m0, s5
	s_add_u32 s5, s16, 0x1000
	s_nop 0
	global_load_lds_dwordx4 v[250:251], off
	v_lshl_add_u64 v[250:251], v[68:69], 0, s[8:9]
	s_mov_b32 m0, s5
	s_add_u32 s5, s16, 0x2000
	s_nop 0
	global_load_lds_dwordx4 v[250:251], off
	v_lshl_add_u64 v[250:251], v[70:71], 0, s[8:9]
	s_mov_b32 m0, s5
	s_add_u32 s5, s16, 0x3000
	s_nop 0
	global_load_lds_dwordx4 v[250:251], off
	v_lshl_add_u64 v[250:251], v[72:73], 0, s[8:9]
	s_mov_b32 m0, s5
	s_add_u32 s5, s16, 0x4000
	s_nop 0
	global_load_lds_dwordx4 v[250:251], off
	v_lshl_add_u64 v[250:251], v[66:67], 0, s[2:3]
	s_mov_b32 m0, s5
	s_add_u32 s5, s16, 0x5000
	s_nop 0
	global_load_lds_dwordx4 v[250:251], off
	v_lshl_add_u64 v[250:251], v[74:75], 0, s[2:3]
	s_mov_b32 m0, s5
	s_add_u32 s5, s16, 0x6000
	s_nop 0
	global_load_lds_dwordx4 v[250:251], off
	v_lshl_add_u64 v[250:251], v[76:77], 0, s[2:3]
	s_mov_b32 m0, s5
	s_add_u32 s5, s16, 0x7000
	s_nop 0
	global_load_lds_dwordx4 v[250:251], off
	v_lshl_add_u64 v[250:251], v[78:79], 0, s[2:3]
	s_mov_b32 m0, s5
	s_add_u32 s5, s16, 0x8000
	s_nop 0
	global_load_lds_dwordx4 v[250:251], off
	v_mov_b32_e32 v250, 0
	s_mov_b32 s100, 1

.LBB0_449:
	s_add_i32 s25, s93, s85
	s_cmpk_lg_u32 s33, 0x200
	s_cbranch_scc1 .Lrm_done_9
	s_sub_i32 s0, 0x1840, s93
	s_cmpk_gt_i32 s0, 0x1ff
	s_cbranch_scc1 .Lrm_done_9
	s_cmpk_lt_i32 s0, 8
	s_cbranch_scc1 .Lrm_done_9
	s_lshr_b32 s0, s0, 3
	s_and_b32 s1, s85, 63
	s_movk_i32 s25, 0x1840
	s_cmp_ge_u32 s1, s0
	s_cbranch_scc1 .Lrm_done_9
	s_lshr_b32 s25, s85, 6
	s_mul_i32 s25, s25, s0
	s_add_i32 s25, s25, s1
	s_add_i32 s25, s25, s93
.Lrm_done_9:
	s_add_i32 s24, s25, 0xfffff140
	s_cmpk_gt_i32 s25, 0x183f
	s_cbranch_scc1 .LBB0_448
	s_cmpk_gt_i32 s25, 0x7ff
	s_mov_b64 s[0:1], -1
	s_cbranch_scc0 .LBB0_511
	s_cmpk_gt_u32 s25, 0xebf
	s_cbranch_scc0 .LBB0_472
	s_add_i32 s29, s25, 0xfffff140
	s_lshr_b32 s28, s29, 3
	s_lshl_b32 s17, s28, 7
	s_cmpk_gt_u32 s29, 0x8ff
	s_mov_b64 s[2:3], -1
	s_mov_b64 s[22:23], -1
	s_cbranch_scc0 .LBB0_456
	v_mov_b32_e32 v0, v111
	s_movk_i32 s0, 0x80
	s_nop 0
	v_cmp_gt_i32_e32 vcc, s0, v0
	s_and_saveexec_b64 s[0:1], vcc
	v_lshl_add_u32 v0, v0, 2, v157
	ds_write_b32 v0, v121
	s_or_b64 exec, exec, s[0:1]
	s_add_i32 s86, s17, 0xffff7000
	s_lshl_b64 s[0:1], s[86:87], 9
	s_add_u32 s4, s72, s0
	s_addc_u32 s5, s73, s1
	s_lshr_b32 s86, s86, 8
	s_and_b32 s0, s17, 0x80
	s_mov_b64 s[22:23], 0

.LBB0_1039:
	s_add_i32 s10, s29, s85
	s_cmpk_lg_u32 s33, 0x200
	s_cbranch_scc1 .Lrm_done_2
	s_sub_i32 s0, 0x2d00, s29
	s_cmpk_gt_i32 s0, 0x1ff
	s_cbranch_scc1 .Lrm_done_2
	s_cmpk_lt_i32 s0, 8
	s_cbranch_scc1 .Lrm_done_2
	s_lshr_b32 s0, s0, 3
	s_and_b32 s11, s85, 63
	s_movk_i32 s10, 0x2d00
	s_cmp_ge_u32 s11, s0
	s_cbranch_scc1 .Lrm_done_2
	s_lshr_b32 s10, s85, 6
	s_mul_i32 s10, s10, s0
	s_add_i32 s10, s10, s11
	s_add_i32 s10, s10, s29
.Lrm_done_2:
	s_cmpk_gt_i32 s10, 0x2cff
	s_cbranch_scc1 .LBB0_1038
	s_ashr_i32 s0, s10, 6
	s_mul_hi_i32 s11, s0, 0x66666667
	s_lshr_b32 s16, s11, 31
	s_ashr_i32 s11, s11, 1
	s_add_i32 s11, s11, s16
	s_mul_i32 s16, s11, 5
	s_sub_i32 s0, s0, s16
	s_lshl_b32 s20, s0, 3
	s_and_b32 s0, s10, 7
	s_lshl_b32 s10, s10, 4
	s_lshl_b32 s11, s11, 10
	s_and_b32 s10, s10, 0x380
	s_or_b32 s10, s11, s10
	s_ashr_i32 s11, s10, 31
	s_or_b32 s16, s20, s0
	s_lshl_b64 s[18:19], s[10:11], 11
	s_add_u32 s18, s1, s18
	s_addc_u32 s19, s24, s19
	s_ashr_i32 s17, s16, 31
	v_mov_b32_e32 v4, v111
	s_lshl_b64 s[22:23], s[16:17], 18
	s_add_u32 s22, s25, s22
	v_ashrrev_i32_e32 v0, 3, v4
	v_lshrrev_b32_e32 v6, 4, v4
	v_xor_b32_e32 v8, v6, v4
	v_ashrrev_i32_e32 v1, 31, v0
	s_addc_u32 s23, s26, s23
	v_lshlrev_b64 v[0:1], 11, v[0:1]
	v_lshlrev_b32_e32 v8, 4, v8
	v_lshl_add_u64 v[2:3], s[18:19], 0, v[0:1]
	v_and_b32_e32 v108, 0x70, v8
	v_lshl_add_u64 v[0:1], s[22:23], 0, v[0:1]
	s_waitcnt vmcnt(11)
	v_lshlrev_b32_e32 v83, 4, v4
	v_lshl_add_u64 v[66:67], v[0:1], 0, v[108:109]
	v_readfirstlane_b32 s11, v83
	v_add_u32_e32 v0, 0x1000, v83
	v_lshl_add_u64 v[64:65], v[2:3], 0, v[108:109]
	s_mov_b32 m0, s11
	s_mov_b64 s[18:19], 0x10000
	v_readfirstlane_b32 s11, v0
	v_add_u32_e32 v0, 0x2000, v83
	s_cmp_eq_u32 s100, 1
	s_cbranch_scc1 .Lpf_g_skip0
	global_load_lds_dwordx4 v[64:65], off

.LBB0_1041:
	s_add_i32 s21, s11, 0xffff8000
	s_and_b32 s21, s21, 0x8000
	s_xor_b32 s17, s21, 0x8000
	s_add_u32 s17, s17, s22
	s_mov_b32 s18, s17
	s_mov_b32 m0, s18
	s_add_u32 s18, s17, 0x1000
	v_add_u32_e32 v85, s21, v80
	global_load_lds_dwordx4 v[64:65], off
	v_lshl_add_u64 v[64:65], v[64:65], 0, s[98:99]
	s_mov_b32 m0, s18
	s_add_u32 s18, s17, 0x2000
	v_or_b32_e32 v106, s21, v81
	global_load_lds_dwordx4 v[68:69], off
	v_lshl_add_u64 v[68:69], v[68:69], 0, s[98:99]
	s_mov_b32 m0, s18
	s_add_u32 s18, s17, 0x3000
	v_add_u32_e32 v250, v85, v84
	global_load_lds_dwordx4 v[70:71], off
	v_lshl_add_u64 v[70:71], v[70:71], 0, s[98:99]
	s_mov_b32 m0, s18
	s_add_u32 s18, s17, 0x4000
	v_add_u32_e32 v251, v106, v84
	global_load_lds_dwordx4 v[72:73], off
	v_lshl_add_u64 v[72:73], v[72:73], 0, s[98:99]
	s_mov_b32 m0, s18
	s_add_u32 s18, s17, 0x5000
	v_add_u32_e32 v252, v85, v82
	global_load_lds_dwordx4 v[66:67], off
	v_lshl_add_u64 v[66:67], v[66:67], 0, s[98:99]
	s_mov_b32 m0, s18
	s_add_u32 s18, s17, 0x6000
	v_add_u32_e32 v253, v106, v82
	global_load_lds_dwordx4 v[74:75], off
	v_lshl_add_u64 v[74:75], v[74:75], 0, s[98:99]
	s_mov_b32 m0, s18
	s_add_u32 s18, s17, 0x7000
	s_nop 0
	global_load_lds_dwordx4 v[76:77], off
	v_lshl_add_u64 v[76:77], v[76:77], 0, s[98:99]
	s_mov_b32 m0, s18
	s_add_u32 s18, s17, 0x8000
	s_nop 0
	global_load_lds_dwordx4 v[78:79], off
	v_lshl_add_u64 v[78:79], v[78:79], 0, s[98:99]
	ds_read_b128 v[86:89], v250
	ds_read_b128 v[102:105], v251 offset:16384
	ds_read_b128 v[122:125], v251 offset:18432
	ds_read_b128 v[126:129], v251 offset:20480
	ds_read_b128 v[130:133], v251 offset:22528
	ds_read_b128 v[90:93], v250 offset:2048
	ds_read_b128 v[94:97], v250 offset:4096
	ds_read_b128 v[98:101], v250 offset:6144
	ds_read_b128 v[218:221], v252
	ds_read_b128 v[234:237], v253 offset:16384
	ds_read_b128 v[238:241], v253 offset:18432
	ds_read_b128 v[242:245], v253 offset:20480
	ds_read_b128 v[246:249], v253 offset:22528
	ds_read_b128 v[222:225], v252 offset:2048
	ds_read_b128 v[226:229], v252 offset:4096
	s_waitcnt lgkmcnt(13)
	v_mfma_f32_16x16x32_bf16 v[60:63], v[102:105], v[86:89], v[60:63]
	ds_read_b128 v[230:233], v252 offset:6144
	s_waitcnt lgkmcnt(13)
	v_mfma_f32_16x16x32_bf16 v[56:59], v[122:125], v[86:89], v[56:59]
	s_waitcnt lgkmcnt(12)
	v_mfma_f32_16x16x32_bf16 v[52:55], v[126:129], v[86:89], v[52:55]
	s_waitcnt lgkmcnt(11)
	v_mfma_f32_16x16x32_bf16 v[48:51], v[130:133], v[86:89], v[48:51]
	s_waitcnt lgkmcnt(10)
	v_mfma_f32_16x16x32_bf16 v[44:47], v[102:105], v[90:93], v[44:47]
	v_mfma_f32_16x16x32_bf16 v[40:43], v[122:125], v[90:93], v[40:43]
	v_mfma_f32_16x16x32_bf16 v[36:39], v[126:129], v[90:93], v[36:39]
	v_mfma_f32_16x16x32_bf16 v[32:35], v[130:133], v[90:93], v[32:35]
	s_waitcnt lgkmcnt(9)
	v_mfma_f32_16x16x32_bf16 v[28:31], v[102:105], v[94:97], v[28:31]
	v_mfma_f32_16x16x32_bf16 v[24:27], v[122:125], v[94:97], v[24:27]
	v_mfma_f32_16x16x32_bf16 v[20:23], v[126:129], v[94:97], v[20:23]
	v_mfma_f32_16x16x32_bf16 v[16:19], v[130:133], v[94:97], v[16:19]
	s_waitcnt lgkmcnt(8)
	v_mfma_f32_16x16x32_bf16 v[12:15], v[102:105], v[98:101], v[12:15]
	v_mfma_f32_16x16x32_bf16 v[8:11], v[122:125], v[98:101], v[8:11]
	v_mfma_f32_16x16x32_bf16 v[4:7], v[126:129], v[98:101], v[4:7]
	v_mfma_f32_16x16x32_bf16 v[0:3], v[130:133], v[98:101], v[0:3]
	s_waitcnt lgkmcnt(6)
	v_mfma_f32_16x16x32_bf16 v[60:63], v[234:237], v[218:221], v[60:63]
	s_waitcnt lgkmcnt(5)
	v_mfma_f32_16x16x32_bf16 v[56:59], v[238:241], v[218:221], v[56:59]
	s_waitcnt lgkmcnt(4)
	v_mfma_f32_16x16x32_bf16 v[52:55], v[242:245], v[218:221], v[52:55]
	s_waitcnt lgkmcnt(3)
	v_mfma_f32_16x16x32_bf16 v[48:51], v[246:249], v[218:221], v[48:51]
	s_waitcnt lgkmcnt(2)
	v_mfma_f32_16x16x32_bf16 v[44:47], v[234:237], v[222:225], v[44:47]
	v_mfma_f32_16x16x32_bf16 v[40:43], v[238:241], v[222:225], v[40:43]
	v_mfma_f32_16x16x32_bf16 v[36:39], v[242:245], v[222:225], v[36:39]
	v_mfma_f32_16x16x32_bf16 v[32:35], v[246:249], v[222:225], v[32:35]
	s_waitcnt lgkmcnt(1)
	v_mfma_f32_16x16x32_bf16 v[28:31], v[234:237], v[226:229], v[28:31]
	v_mfma_f32_16x16x32_bf16 v[24:27], v[238:241], v[226:229], v[24:27]
	v_mfma_f32_16x16x32_bf16 v[20:23], v[242:245], v[226:229], v[20:23]
	v_mfma_f32_16x16x32_bf16 v[16:19], v[246:249], v[226:229], v[16:19]
	s_waitcnt lgkmcnt(0)
	v_mfma_f32_16x16x32_bf16 v[12:15], v[234:237], v[230:233], v[12:15]
	v_mfma_f32_16x16x32_bf16 v[8:11], v[238:241], v[230:233], v[8:11]
	v_mfma_f32_16x16x32_bf16 v[4:7], v[242:245], v[230:233], v[4:7]
	v_mfma_f32_16x16x32_bf16 v[0:3], v[246:249], v[230:233], v[0:3]
	s_add_i32 s11, s11, 0x8000
	s_cmp_lg_u32 s11, 0x80000
	s_waitcnt vmcnt(0)
	s_barrier
	s_cbranch_scc1 .LBB0_1041
	s_mov_b32 s100, 0
	s_add_i32 s17, s29, s33
	s_add_i32 s11, s17, s85
	s_cmpk_lg_u32 s33, 0x200
	s_cbranch_scc1 .Lrm_done_6
	s_sub_i32 s18, 0x2d00, s17
	s_cmpk_gt_i32 s18, 0x1ff
	s_cbranch_scc1 .Lrm_done_6
	s_cmpk_lt_i32 s18, 8
	s_cbranch_scc1 .Lrm_done_6
	s_lshr_b32 s18, s18, 3
	s_and_b32 s19, s85, 63
	s_movk_i32 s11, 0x2d00
	s_cmp_ge_u32 s19, s18
	s_cbranch_scc1 .Lrm_done_6
	s_lshr_b32 s11, s85, 6
	s_mul_i32 s11, s11, s18
	s_add_i32 s11, s11, s19
	s_add_i32 s11, s11, s17
.Lrm_done_6:
	s_cmpk_gt_i32 s11, 0x2cff
	s_cbranch_scc1 .Lpf_g_done
	s_ashr_i32 s17, s11, 6
	s_mul_hi_i32 s18, s17, 0x66666667
	s_lshr_b32 s19, s18, 31
	s_ashr_i32 s18, s18, 1
	s_add_i32 s18, s18, s19
	s_mul_i32 s19, s18, 5
	s_sub_i32 s17, s17, s19
	s_lshl_b32 s17, s17, 3
	s_and_b32 s19, s11, 7
	s_or_b32 s17, s17, s19
	s_lshl_b32 s18, s18, 10
	s_lshl_b32 s19, s11, 4
	s_and_b32 s19, s19, 0x380
	s_or_b32 s18, s18, s19
	s_sub_i32 s18, s18, s10
	s_or_b32 s19, s20, s0
	s_sub_i32 s17, s17, s19
	s_ashr_i32 s19, s18, 31
	s_lshl_b64 s[18:19], s[18:19], 11
	s_sub_u32 s18, s18, 0x800
	s_subb_u32 s19, s19, 0
	s_mov_b32 s98, s17
	s_ashr_i32 s99, s98, 31
	s_lshl_b64 s[98:99], s[98:99], 18
	s_sub_u32 s98, s98, 0x800
	s_subb_u32 s99, s99, 0
	v_lshl_add_u64 v[250:251], v[64:65], 0, s[18:19]
	s_mov_b32 s11, s22
	s_mov_b32 m0, s11
	s_add_u32 s11, s22, 0x1000
	s_nop 0
	global_load_lds_dwordx4 v[250:251], off
	v_lshl_add_u64 v[250:251], v[68:69], 0, s[18:19]
	s_mov_b32 m0, s11
	s_add_u32 s11, s22, 0x2000
	s_nop 0
	global_load_lds_dwordx4 v[250:251], off
	v_lshl_add_u64 v[250:251], v[70:71], 0, s[18:19]
	s_mov_b32 m0, s11
	s_add_u32 s11, s22, 0x3000
	s_nop 0
	global_load_lds_dwordx4 v[250:251], off
	v_lshl_add_u64 v[250:251], v[72:73], 0, s[18:19]
	s_mov_b32 m0, s11
	s_add_u32 s11, s22, 0x4000
	s_nop 0
	global_load_lds_dwordx4 v[250:251], off
	v_lshl_add_u64 v[250:251], v[66:67], 0, s[98:99]
	s_mov_b32 m0, s11
	s_add_u32 s11, s22, 0x5000
	s_nop 0
	global_load_lds_dwordx4 v[250:251], off
	v_lshl_add_u64 v[250:251], v[74:75], 0, s[98:99]
	s_mov_b32 m0, s11
	s_add_u32 s11, s22, 0x6000
	s_nop 0
	global_load_lds_dwordx4 v[250:251], off
	v_lshl_add_u64 v[250:251], v[76:77], 0, s[98:99]
	s_mov_b32 m0, s11
	s_add_u32 s11, s22, 0x7000
	s_nop 0
	global_load_lds_dwordx4 v[250:251], off
	v_lshl_add_u64 v[250:251], v[78:79], 0, s[98:99]
	s_mov_b32 m0, s11
	s_add_u32 s11, s22, 0x8000
	s_nop 0
	global_load_lds_dwordx4 v[250:251], off
	v_mov_b32_e32 v250, 0
	s_mov_b32 s100, 1

.LBB0_1094:
	s_add_i32 s8, s94, s85
	s_cmpk_lg_u32 s33, 0x200
	s_cbranch_scc1 .Lrm_done_3
	s_sub_i32 s9, 0x900, s94
	s_cmpk_gt_i32 s9, 0x1ff
	s_cbranch_scc1 .Lrm_done_3
	s_cmpk_lt_i32 s9, 8
	s_cbranch_scc1 .Lrm_done_3
	s_lshr_b32 s9, s9, 3
	s_and_b32 s26, s85, 63
	s_movk_i32 s8, 0x900
	s_cmp_ge_u32 s26, s9
	s_cbranch_scc1 .Lrm_done_3
	s_lshr_b32 s8, s85, 6
	s_mul_i32 s8, s8, s9
	s_add_i32 s8, s8, s26
	s_add_i32 s8, s8, s94
.Lrm_done_3:
	s_cmpk_gt_i32 s8, 0x8ff
	s_cbranch_scc1 .LBB0_1093
	s_lshl_b32 s9, s8, 4
	s_and_b32 s26, s8, 7
	s_and_b32 s8, s9, 0xffffff80
	s_ashr_i32 s9, s8, 31
	s_lshl_b64 s[22:23], s[8:9], 10
	s_add_u32 s10, s55, s22
	s_addc_u32 s11, s56, s23
	s_lshl_b32 s24, s26, 17
	s_add_u32 s16, s57, s24
	s_addc_u32 s17, s60, 0
	s_lshl_b64 s[18:19], s[8:9], 11
	s_add_u32 s18, s62, s18
	s_addc_u32 s19, s64, s19
	s_lshl_b32 s9, s26, 18
	s_add_u32 s20, s90, s9
	s_addc_u32 s21, s91, 0
	s_add_u32 s22, s92, s22
	s_addc_u32 s23, s93, s23
	s_add_u32 s24, s0, s24
	s_addc_u32 s25, s58, 0
	s_lshl_b32 s9, s26, 7
	v_mov_b32_e32 v65, 0
	s_mov_b32 s68, 0
	v_mov_b32_e32 v64, 0
	v_mov_b32_e32 v67, 0
	v_mov_b32_e32 v66, 0
	v_mov_b32_e32 v69, 0
	v_mov_b32_e32 v68, 0
	v_mov_b32_e32 v71, 0
	v_mov_b32_e32 v70, 0
	v_mov_b32_e32 v73, 0
	v_mov_b32_e32 v72, 0
	v_mov_b32_e32 v75, 0
	v_mov_b32_e32 v74, 0
	v_mov_b32_e32 v77, 0
	v_mov_b32_e32 v76, 0
	v_mov_b32_e32 v79, 0
	v_mov_b32_e32 v78, 0
	s_waitcnt vmcnt(11)
	v_mov_b32_e32 v81, 0
	v_mov_b32_e32 v80, 0
	v_mov_b32_e32 v83, 0
	v_mov_b32_e32 v82, 0
	s_waitcnt vmcnt(10)
	v_mov_b32_e32 v85, 0
	v_mov_b32_e32 v84, 0
	v_mov_b32_e32 v87, 0
	v_mov_b32_e32 v86, 0
	s_waitcnt vmcnt(9)
	v_mov_b32_e32 v89, 0
	v_mov_b32_e32 v88, 0
	v_mov_b32_e32 v91, 0
	v_mov_b32_e32 v90, 0
	s_waitcnt vmcnt(8)
	v_mov_b32_e32 v93, 0
	v_mov_b32_e32 v92, 0
	v_mov_b32_e32 v95, 0
	v_mov_b32_e32 v94, 0

.LBB0_1147:
	s_add_i32 s2, s23, s85
	s_cmpk_lg_u32 s33, 0x200
	s_cbranch_scc1 .Lrm_done_4
	s_sub_i32 s10, 0x900, s23
	s_cmpk_gt_i32 s10, 0x1ff
	s_cbranch_scc1 .Lrm_done_4
	s_cmpk_lt_i32 s10, 8
	s_cbranch_scc1 .Lrm_done_4
	s_lshr_b32 s10, s10, 3
	s_and_b32 s0, s85, 63
	s_movk_i32 s2, 0x900
	s_cmp_ge_u32 s0, s10
	s_cbranch_scc1 .Lrm_done_4
	s_lshr_b32 s2, s85, 6
	s_mul_i32 s2, s2, s10
	s_add_i32 s2, s2, s0
	s_add_i32 s2, s2, s23
.Lrm_done_4:
	s_cmpk_gt_i32 s2, 0x8ff
	s_cbranch_scc1 .LBB0_1146
	s_lshl_b32 s10, s2, 4
	s_and_b32 s0, s2, 7
	s_and_b32 s2, s10, 0xffffff80
	s_ashr_i32 s3, s2, 31
	s_lshl_b64 s[16:17], s[2:3], 11
	s_add_u32 s16, s1, s16
	v_mov_b32_e32 v4, v111
	s_addc_u32 s17, s18, s17
	s_lshl_b32 s3, s0, 18
	s_add_u32 s24, s19, s3
	v_ashrrev_i32_e32 v0, 3, v4
	v_lshrrev_b32_e32 v6, 4, v4
	v_xor_b32_e32 v8, v6, v4
	v_ashrrev_i32_e32 v1, 31, v0
	s_addc_u32 s25, s20, 0
	v_lshlrev_b64 v[0:1], 11, v[0:1]
	v_lshlrev_b32_e32 v8, 4, v8
	v_lshl_add_u64 v[2:3], s[16:17], 0, v[0:1]
	v_and_b32_e32 v108, 0x70, v8
	v_lshl_add_u64 v[0:1], s[24:25], 0, v[0:1]
	s_waitcnt vmcnt(11)
	v_lshlrev_b32_e32 v83, 4, v4
	v_lshl_add_u64 v[66:67], v[0:1], 0, v[108:109]
	v_readfirstlane_b32 s3, v83
	v_add_u32_e32 v0, 0x1000, v83
	v_lshl_add_u64 v[64:65], v[2:3], 0, v[108:109]
	s_mov_b32 m0, s3
	s_mov_b64 s[16:17], 0x10000
	v_readfirstlane_b32 s3, v0
	v_add_u32_e32 v0, 0x2000, v83
	global_load_lds_dwordx4 v[64:65], off
	v_lshl_add_u64 v[68:69], v[64:65], 0, s[16:17]
	s_mov_b32 m0, s3
	s_mov_b64 s[24:25], 0x20000
	v_readfirstlane_b32 s3, v0
	v_add_u32_e32 v0, 0x3000, v83
	global_load_lds_dwordx4 v[68:69], off
	v_lshl_add_u64 v[70:71], v[64:65], 0, s[24:25]
	s_mov_b32 m0, s3
	s_mov_b64 s[26:27], 0x30000
	v_readfirstlane_b32 s3, v0
	v_add_u32_e32 v0, 0x4000, v83
	global_load_lds_dwordx4 v[70:71], off
	v_lshl_add_u64 v[72:73], v[64:65], 0, s[26:27]
	s_mov_b32 m0, s3
	v_readfirstlane_b32 s3, v0
	v_add_u32_e32 v0, 0x5000, v83
	global_load_lds_dwordx4 v[72:73], off
	s_mov_b32 m0, s3
	v_readfirstlane_b32 s3, v0
	v_add_u32_e32 v0, 0x6000, v83
	global_load_lds_dwordx4 v[66:67], off
	v_lshl_add_u64 v[74:75], v[66:67], 0, s[16:17]
	s_mov_b32 m0, s3
	v_readfirstlane_b32 s3, v0
	v_add_u32_e32 v0, 0x7000, v83
	global_load_lds_dwordx4 v[74:75], off
	v_lshl_add_u64 v[76:77], v[66:67], 0, s[24:25]
	s_mov_b32 m0, s3
	v_readfirstlane_b32 s3, v0
	global_load_lds_dwordx4 v[76:77], off
	v_lshl_add_u64 v[78:79], v[66:67], 0, s[26:27]
	s_mov_b32 m0, s3
	v_and_b32_e32 v5, 15, v4
	global_load_lds_dwordx4 v[78:79], off
	v_lshrrev_b32_e32 v0, 1, v4
	v_and_or_b32 v0, v0, s84, v5
	v_lshlrev_b32_e32 v80, 7, v0
	v_lshlrev_b32_e32 v0, 7, v4
	v_bfe_u32 v7, v4, 4, 2
	v_and_b32_e32 v81, 0x2780, v0
	v_bfe_u32 v0, v4, 1, 3
	v_bitop3_b32 v1, v6, v0, 3 bitop3:0x6c
	v_bitop3_b32 v0, v7, v0, 4 bitop3:0x36
	v_lshlrev_b32_e32 v82, 4, v0
	v_mov_b32_e32 v0, 0
	s_waitcnt vmcnt(0)
	v_lshlrev_b32_e32 v84, 4, v1
	s_mov_b32 s11, 0
	s_mov_b32 s3, 0x8000
	v_mov_b32_e32 v1, v0
	v_mov_b32_e32 v2, v0
	v_mov_b32_e32 v3, v0
	v_mov_b32_e32 v4, v0
	v_mov_b32_e32 v5, v0
	v_mov_b32_e32 v6, v0
	v_mov_b32_e32 v7, v0
	v_mov_b32_e32 v8, v0
	v_mov_b32_e32 v9, v0
	v_mov_b32_e32 v10, v0
	v_mov_b32_e32 v11, v0
	v_mov_b32_e32 v12, v0
	v_mov_b32_e32 v13, v0
	v_mov_b32_e32 v14, v0
	v_mov_b32_e32 v15, v0
	v_mov_b32_e32 v16, v0
	v_mov_b32_e32 v17, v0
	v_mov_b32_e32 v18, v0
	v_mov_b32_e32 v19, v0
	v_mov_b32_e32 v20, v0
	v_mov_b32_e32 v21, v0
	v_mov_b32_e32 v22, v0
	v_mov_b32_e32 v23, v0
	v_mov_b32_e32 v24, v0
	v_mov_b32_e32 v25, v0
	v_mov_b32_e32 v26, v0
	v_mov_b32_e32 v27, v0
	v_mov_b32_e32 v28, v0
	v_mov_b32_e32 v29, v0
	v_mov_b32_e32 v30, v0
	v_mov_b32_e32 v31, v0
	v_mov_b32_e32 v32, v0
	v_mov_b32_e32 v33, v0
	v_mov_b32_e32 v34, v0
	v_mov_b32_e32 v35, v0
	v_mov_b32_e32 v36, v0
	v_mov_b32_e32 v37, v0
	v_mov_b32_e32 v38, v0
	v_mov_b32_e32 v39, v0
	v_mov_b32_e32 v40, v0
	v_mov_b32_e32 v41, v0
	v_mov_b32_e32 v42, v0
	v_mov_b32_e32 v43, v0
	v_mov_b32_e32 v44, v0
	v_mov_b32_e32 v45, v0
	v_mov_b32_e32 v46, v0
	v_mov_b32_e32 v47, v0
	v_mov_b32_e32 v48, v0
	v_mov_b32_e32 v49, v0
	v_mov_b32_e32 v50, v0
	v_mov_b32_e32 v51, v0
	v_mov_b32_e32 v52, v0
	v_mov_b32_e32 v53, v0
	v_mov_b32_e32 v54, v0
	v_mov_b32_e32 v55, v0
	v_mov_b32_e32 v56, v0
	v_mov_b32_e32 v57, v0
	v_mov_b32_e32 v58, v0
	v_mov_b32_e32 v59, v0
	v_mov_b32_e32 v60, v0
	v_mov_b32_e32 v61, v0
	v_mov_b32_e32 v62, v0
	v_mov_b32_e32 v63, v0
	s_waitcnt lgkmcnt(0)
	s_barrier
	v_readfirstlane_b32 s25, v83
	s_mov_b64 s[98:99], 0x80
	v_lshl_add_u64 v[64:65], v[64:65], 0, s[98:99]
	v_lshl_add_u64 v[68:69], v[68:69], 0, s[98:99]
	v_lshl_add_u64 v[70:71], v[70:71], 0, s[98:99]
	v_lshl_add_u64 v[72:73], v[72:73], 0, s[98:99]
	v_lshl_add_u64 v[66:67], v[66:67], 0, s[98:99]
	v_lshl_add_u64 v[74:75], v[74:75], 0, s[98:99]
	v_lshl_add_u64 v[76:77], v[76:77], 0, s[98:99]
	v_lshl_add_u64 v[78:79], v[78:79], 0, s[98:99]
